# v125 + P2 step 2 tiles 2..7: all four B fragments of a tile fetched up front (counted waits 3,2,1,0)
# baseline (speedup 1.0000x reference)
; #define LAS __attribute__((address_space(3)))
; template <int SKIP>
; __device__ __forceinline__ void p2_chunk_prep_fast(Frame& F, const Args& a) {
;     ...
;                 if (kind == 0) {
;                     if (tj > ti) continue;
;                     f32x4 acc = (f32x4){0.f, 0.f, 0.f, 0.f};
; #pragma unroll
;                     for (int ks = 0; ks < 4; ++ks) acc = __builtin_amdgcn_mfma_f32_16x16x32_bf16(af[ks], *(const LAS bf16x8_t*)(L + L_KS + (16 * tj + fr) * QS_LD + (32 * ks + 8 * fq) * 2), acc, 0, 0, 0);
;                     const int j = 16 * tj + fr; const float gj = gc[j]; const f32x4 gi4 = *(const LAS f32x4*)(gc + 16 * ti + 4 * fq), bi4 = *(const LAS f32x4*)(beta + 16 * ti + 4 * fq);
; #pragma unroll
;                     for (int r = 0; r < 4; ++r) { const int i = 16 * ti + 4 * fq + r; const float m = (tj < ti || fr < 4 * fq + r) ? 1.f : 0.f; Am[i * AM_LD + j] = acc[r] * bi4[r] * __expf(fminf(gi4[r] - gj, 0.f)) * m; }
.Lst2_n6:
	s_and_b64 vcc, exec, s[6:7]
	v_lshlrev_b32_e32 v70, 2, v83
	s_cbranch_vccz .LBB0_677
	v_mad_u32_u24 v63, v83, s28, v72
	ds_read_b128 v[84:87], v63 offset:17408
	ds_read_b128 v[88:91], v63 offset:17472
	ds_read_b128 v[96:99], v63 offset:17536
	ds_read_b128 v[100:103], v63 offset:17600
	v_cmp_lt_i32_e32 vcc, v83, v67
	s_or_b64 s[6:7], s[70:71], vcc
	v_cmp_le_i32_e32 vcc, v83, v67
	s_waitcnt lgkmcnt(3)
	v_mfma_f32_16x16x32_bf16 v[84:87], v[58:61], v[84:87], 0
	v_cndmask_b32_e64 v64, 0, 1.0, s[6:7]
	s_or_b64 s[6:7], s[70:71], vcc
	s_waitcnt lgkmcnt(2)
	v_mfma_f32_16x16x32_bf16 v[84:87], v[54:57], v[88:91], v[84:87]
	s_waitcnt lgkmcnt(1)
	v_mfma_f32_16x16x32_bf16 v[84:87], v[50:53], v[96:99], v[84:87]
	v_add_u32_e32 v63, 0, v70
	v_add_u32_e32 v63, 0x20500, v63
	s_waitcnt lgkmcnt(0)
	v_mfma_f32_16x16x32_bf16 v[84:87], v[46:49], v[100:103], v[84:87]
	ds_read_b32 v63, v63
	ds_read_b128 v[88:91], v73
	ds_read_b128 v[92:95], v74
	s_waitcnt lgkmcnt(1)
	v_sub_f32_e32 v76, v88, v63
	v_sub_f32_e32 v78, v89, v63
	v_min_f32_e32 v76, 0, v76
	v_min_f32_e32 v78, 0, v78
	v_mul_f32_e32 v76, 0x3fb8aa3b, v76
	v_mul_f32_e32 v78, 0x3fb8aa3b, v78
	v_exp_f32_e32 v76, v76
	v_exp_f32_e32 v78, v78
	s_waitcnt lgkmcnt(0)
	v_mul_f32_e32 v65, v84, v92
	v_mul_f32_e32 v77, v85, v93
	v_mul_f32_e32 v65, v65, v76
	v_cndmask_b32_e64 v76, 0, 1.0, s[6:7]
	v_mul_f32_e32 v77, v77, v78
	v_mul_f32_e32 v76, v76, v77
	v_sub_f32_e32 v77, v90, v63
	v_min_f32_e32 v77, 0, v77
	v_mul_f32_e32 v64, v64, v65
	v_mul_lo_u32 v65, v69, s28
	v_mul_f32_e32 v77, 0x3fb8aa3b, v77
	v_add3_u32 v65, s29, v70, v65
	v_exp_f32_e32 v77, v77
	ds_write2_b32 v65, v64, v76 offset1:68
	v_or_b32_e32 v64, 2, v67
	v_sub_f32_e32 v63, v91, v63
	v_cmp_lt_i32_e32 vcc, v83, v64
	v_min_f32_e32 v63, 0, v63
	s_or_b64 s[6:7], s[70:71], vcc
	v_mul_f32_e32 v76, v86, v94
	v_mul_f32_e32 v63, 0x3fb8aa3b, v63
	v_cndmask_b32_e64 v64, 0, 1.0, s[6:7]
	v_mul_f32_e32 v76, v76, v77
	v_exp_f32_e32 v63, v63
	v_mul_f32_e32 v64, v64, v76
	v_or_b32_e32 v76, 3, v67
	v_cmp_lt_i32_e32 vcc, v83, v76
	s_or_b64 s[6:7], s[70:71], vcc
	v_mul_f32_e32 v77, v87, v95
	v_cndmask_b32_e64 v76, 0, 1.0, s[6:7]
	v_mul_f32_e32 v63, v77, v63
	v_mul_f32_e32 v63, v76, v63
	ds_write2_b32 v65, v64, v63 offset0:136 offset1:204

; #define LAS __attribute__((address_space(3)))
; __device__ __forceinline__ u32x2_t pack4bf(f32x4 v) { u32x2_t r; r.x = pg8::cvt_pk_bf16(v[0], v[1]); r.y = pg8::cvt_pk_bf16(v[2], v[3]); return r; }
; __device__ __forceinline__ int frag_off(int row, int k, int ksteps) { return ((row >> 4) * ksteps + (k >> 5)) * 512 + (((k >> 3) & 3) * 16 + (row & 15)) * 8 + (k & 7); }
; template <int SKIP>
; __device__ __forceinline__ void p2_chunk_prep_fast(Frame& F, const Args& a) {
;     ...
;                 } else {
;                     const int i = 16 * tj + fr; u32x2_t o = (u32x2_t){0u, 0u};
;                     if (tj >= ti) {
;                         f32x4 acc = (f32x4){0.f, 0.f, 0.f, 0.f};
; #pragma unroll
;                         for (int ks = 0; ks < 4; ++ks) acc = __builtin_amdgcn_mfma_f32_16x16x32_bf16(af[ks], *(const LAS bf16x8_t*)(L + L_QS + (16 * tj + fr) * QS_LD + (32 * ks + 8 * fq) * 2), acc, 0, 0, 0);
;                         const float gi = gc[i]; const f32x4 gj4 = *(const LAS f32x4*)(gc + 16 * ti + 4 * fq);
; #pragma unroll
;                         for (int r = 0; r < 4; ++r) { const float m = (tj > ti || 4 * fq + r <= fr) ? 1.f : 0.f; acc[r] = acc[r] * __expf(fminf(gi - gj4[r], 0.f)) * m; }
;                         o = pack4bf(acc);
;                     }
;                     *(u32x2_t*)(oQK + frag_off(i, 16 * ti + 4 * fq, 2)) = o;
.Lst2_do3:
	v_mov_b32_e32 v64, 0
	s_andn2_b64 vcc, exec, s[72:73]
	v_mov_b32_e32 v65, 0
	s_cbranch_vccnz .LBB0_680
	v_or_b32_e32 v63, 16, v83
	v_mad_u32_u24 v64, v63, s28, v72
	ds_read_b128 v[84:87], v64
	ds_read_b128 v[88:91], v64 offset:64
	ds_read_b128 v[96:99], v64 offset:128
	ds_read_b128 v[100:103], v64 offset:192
	v_lshl_add_u32 v63, v63, 2, 0
	v_add_u32_e32 v63, 0x20500, v63
	v_cmp_gt_i32_e32 vcc, v67, v83
	s_waitcnt lgkmcnt(3)
	v_mfma_f32_16x16x32_bf16 v[84:87], v[58:61], v[84:87], 0
	s_waitcnt lgkmcnt(2)
	v_mfma_f32_16x16x32_bf16 v[84:87], v[54:57], v[88:91], v[84:87]
	s_waitcnt lgkmcnt(1)
	v_mfma_f32_16x16x32_bf16 v[84:87], v[50:53], v[96:99], v[84:87]
	v_cndmask_b32_e64 v64, 1.0, 0, vcc
	v_cmp_lt_i32_e32 vcc, v67, v83
	s_waitcnt lgkmcnt(0)
	v_mfma_f32_16x16x32_bf16 v[84:87], v[46:49], v[100:103], v[84:87]
	ds_read_b32 v63, v63
	ds_read_b128 v[88:91], v75
	v_cndmask_b32_e64 v64, v64, 1.0, s[68:69]
	s_or_b64 s[90:91], s[68:69], vcc
	s_waitcnt lgkmcnt(0)
	v_sub_f32_e32 v65, v63, v88
	v_min_f32_e32 v65, 0, v65
	v_sub_f32_e32 v76, v63, v89
	v_mul_f32_e32 v65, 0x3fb8aa3b, v65
	v_min_f32_e32 v76, 0, v76
	v_exp_f32_e32 v65, v65
	v_mul_f32_e32 v76, 0x3fb8aa3b, v76
	v_exp_f32_e32 v76, v76
	v_sub_f32_e32 v77, v63, v90
	v_min_f32_e32 v77, 0, v77
	v_mul_f32_e32 v65, v84, v65
	v_mul_f32_e32 v77, 0x3fb8aa3b, v77
	v_mul_f32_e32 v64, v64, v65
	v_cndmask_b32_e64 v65, 0, 1.0, s[90:91]
	v_mul_f32_e32 v76, v85, v76
	v_exp_f32_e32 v77, v77
	v_mul_f32_e32 v65, v65, v76
	v_or_b32_e32 v76, 2, v67
	v_sub_f32_e32 v63, v63, v91
	v_cmp_gt_i32_e32 vcc, v76, v83
	v_min_f32_e32 v63, 0, v63
	v_mul_f32_e32 v63, 0x3fb8aa3b, v63
	v_cndmask_b32_e64 v76, 1.0, 0, vcc
	v_cndmask_b32_e64 v76, v76, 1.0, s[68:69]
	v_mul_f32_e32 v77, v86, v77
	v_exp_f32_e32 v63, v63
	v_mul_f32_e32 v76, v76, v77
	v_or_b32_e32 v77, 3, v67
	v_cmp_gt_i32_e32 vcc, v77, v83
	v_mul_f32_e32 v63, v87, v63
	v_cvt_pk_bf16_f32 v64, v64, v65
	v_cndmask_b32_e64 v77, 1.0, 0, vcc
	v_cndmask_b32_e64 v77, v77, 1.0, s[68:69]
	v_mul_f32_e32 v63, v77, v63
	v_cvt_pk_bf16_f32 v65, v76, v63

; #define LAS __attribute__((address_space(3)))
; __device__ __forceinline__ u32x2_t pack4bf(f32x4 v) { u32x2_t r; r.x = pg8::cvt_pk_bf16(v[0], v[1]); r.y = pg8::cvt_pk_bf16(v[2], v[3]); return r; }
; __device__ __forceinline__ int frag_off(int row, int k, int ksteps) { return ((row >> 4) * ksteps + (k >> 5)) * 512 + (((k >> 3) & 3) * 16 + (row & 15)) * 8 + (k & 7); }
; template <int SKIP>
; __device__ __forceinline__ void p2_chunk_prep_fast(Frame& F, const Args& a) {
;     ...
;             for (int tj = 0; tj < 4; ++tj) {
;                 if (kind == 0) {
;                     if (tj > ti) continue;
;                     f32x4 acc = (f32x4){0.f, 0.f, 0.f, 0.f};
; #pragma unroll
;                     for (int ks = 0; ks < 4; ++ks) acc = __builtin_amdgcn_mfma_f32_16x16x32_bf16(af[ks], *(const LAS bf16x8_t*)(L + L_KS + (16 * tj + fr) * QS_LD + (32 * ks + 8 * fq) * 2), acc, 0, 0, 0);
;                     const int j = 16 * tj + fr; const float gj = gc[j]; const f32x4 gi4 = *(const LAS f32x4*)(gc + 16 * ti + 4 * fq), bi4 = *(const LAS f32x4*)(beta + 16 * ti + 4 * fq);
; #pragma unroll
;                     for (int r = 0; r < 4; ++r) { const int i = 16 * ti + 4 * fq + r; const float m = (tj < ti || fr < 4 * fq + r) ? 1.f : 0.f; Am[i * AM_LD + j] = acc[r] * bi4[r] * __expf(fminf(gi4[r] - gj, 0.f)) * m; }
;                 } else {
;                     const int i = 16 * tj + fr; u32x2_t o = (u32x2_t){0u, 0u};
;                     if (tj >= ti) {
;                         f32x4 acc = (f32x4){0.f, 0.f, 0.f, 0.f};
; #pragma unroll
;                         for (int ks = 0; ks < 4; ++ks) acc = __builtin_amdgcn_mfma_f32_16x16x32_bf16(af[ks], *(const LAS bf16x8_t*)(L + L_QS + (16 * tj + fr) * QS_LD + (32 * ks + 8 * fq) * 2), acc, 0, 0, 0);
;                         const float gi = gc[i]; const f32x4 gj4 = *(const LAS f32x4*)(gc + 16 * ti + 4 * fq);
; #pragma unroll
;                         for (int r = 0; r < 4; ++r) { const float m = (tj > ti || 4 * fq + r <= fr) ? 1.f : 0.f; acc[r] = acc[r] * __expf(fminf(gi - gj4[r], 0.f)) * m; }
;                         o = pack4bf(acc);
;                     }
;                     *(u32x2_t*)(oQK + frag_off(i, 16 * ti + 4 * fq, 2)) = o;
.LBB0_681:
	s_and_b64 vcc, exec, s[90:91]
	s_cbranch_vccz .LBB0_684
	s_andn2_b64 vcc, exec, s[70:71]
	s_cbranch_vccnz .LBB0_684
	v_or_b32_e32 v63, 16, v83
	v_mad_u32_u24 v64, v63, s28, v72
	ds_read_b128 v[84:87], v64 offset:17408
	ds_read_b128 v[88:91], v64 offset:17472
	ds_read_b128 v[96:99], v64 offset:17536
	ds_read_b128 v[100:103], v64 offset:17600
	v_lshlrev_b32_e32 v63, 2, v63
	v_cmp_lt_i32_e32 vcc, v83, v67
	s_or_b64 s[90:91], s[74:75], vcc
	s_waitcnt lgkmcnt(3)
	v_mfma_f32_16x16x32_bf16 v[84:87], v[58:61], v[84:87], 0
	v_cndmask_b32_e64 v65, 0, 1.0, s[90:91]
	v_cmp_le_i32_e32 vcc, v83, v67
	s_or_b64 s[90:91], s[74:75], vcc
	s_waitcnt lgkmcnt(2)
	v_mfma_f32_16x16x32_bf16 v[84:87], v[54:57], v[88:91], v[84:87]
	s_waitcnt lgkmcnt(1)
	v_mfma_f32_16x16x32_bf16 v[84:87], v[50:53], v[96:99], v[84:87]
	v_add_u32_e32 v64, 0, v63
	v_add_u32_e32 v64, 0x20500, v64
	s_waitcnt lgkmcnt(0)
	v_mfma_f32_16x16x32_bf16 v[84:87], v[46:49], v[100:103], v[84:87]
	ds_read_b32 v64, v64
	ds_read_b128 v[88:91], v73
	ds_read_b128 v[92:95], v74
	s_waitcnt lgkmcnt(1)
	v_sub_f32_e32 v77, v88, v64
	v_min_f32_e32 v77, 0, v77
	v_mul_f32_e32 v77, 0x3fb8aa3b, v77
	v_sub_f32_e32 v78, v89, v64
	v_exp_f32_e32 v77, v77
	v_min_f32_e32 v78, 0, v78
	v_mul_f32_e32 v78, 0x3fb8aa3b, v78
	v_exp_f32_e32 v78, v78
	s_waitcnt lgkmcnt(0)
	v_mul_f32_e32 v76, v84, v92
	v_mul_f32_e32 v76, v76, v77
	v_mul_f32_e32 v65, v65, v76
	v_mul_lo_u32 v76, v69, s28
	v_mul_f32_e32 v77, v85, v93
	v_add3_u32 v63, s29, v76, v63
	v_cndmask_b32_e64 v76, 0, 1.0, s[90:91]
	v_mul_f32_e32 v77, v77, v78
	v_mul_f32_e32 v76, v76, v77
	v_sub_f32_e32 v77, v90, v64
	v_min_f32_e32 v77, 0, v77
	v_mul_f32_e32 v77, 0x3fb8aa3b, v77
	v_exp_f32_e32 v77, v77
	ds_write2_b32 v63, v65, v76 offset1:68
	v_or_b32_e32 v65, 2, v67
	v_sub_f32_e32 v64, v91, v64
	v_cmp_lt_i32_e32 vcc, v83, v65
	v_min_f32_e32 v64, 0, v64
	s_or_b64 s[90:91], s[74:75], vcc
	v_mul_f32_e32 v76, v86, v94
	v_mul_f32_e32 v64, 0x3fb8aa3b, v64
	v_cndmask_b32_e64 v65, 0, 1.0, s[90:91]
	v_mul_f32_e32 v76, v76, v77
	v_exp_f32_e32 v64, v64
	v_mul_f32_e32 v65, v65, v76
	v_or_b32_e32 v76, 3, v67
	v_cmp_lt_i32_e32 vcc, v83, v76
	s_or_b64 s[90:91], s[74:75], vcc
	v_mul_f32_e32 v77, v87, v95
	v_cndmask_b32_e64 v76, 0, 1.0, s[90:91]
	v_mul_f32_e32 v64, v77, v64
	v_mul_f32_e32 v64, v76, v64
	ds_write2_b32 v63, v65, v64 offset0:136 offset1:204
.LBB0_684:
	s_and_b64 vcc, exec, s[6:7]
	s_mov_b64 s[90:91], -1
	s_cbranch_vccnz .LBB0_688
	v_readlane_b32 s90, v255, 47
	v_readlane_b32 s91, v255, 48
	v_mov_b32_e32 v64, 0
	s_andn2_b64 vcc, exec, s[90:91]
	v_mov_b32_e32 v65, 0
	s_cbranch_vccnz .LBB0_687
	v_or_b32_e32 v63, 32, v83
	v_mad_u32_u24 v64, v63, s28, v72
	ds_read_b128 v[84:87], v64
	ds_read_b128 v[88:91], v64 offset:64
	ds_read_b128 v[96:99], v64 offset:128
	ds_read_b128 v[100:103], v64 offset:192
	v_lshl_add_u32 v63, v63, 2, 0
	v_add_u32_e32 v63, 0x20500, v63
	v_cmp_gt_i32_e32 vcc, v67, v83
	s_waitcnt lgkmcnt(3)
	v_mfma_f32_16x16x32_bf16 v[84:87], v[58:61], v[84:87], 0
	s_waitcnt lgkmcnt(2)
	v_mfma_f32_16x16x32_bf16 v[84:87], v[54:57], v[88:91], v[84:87]
	s_waitcnt lgkmcnt(1)
	v_mfma_f32_16x16x32_bf16 v[84:87], v[50:53], v[96:99], v[84:87]
	v_cndmask_b32_e64 v64, 1.0, 0, vcc
	v_cmp_lt_i32_e32 vcc, v67, v83
	s_waitcnt lgkmcnt(0)
	v_mfma_f32_16x16x32_bf16 v[84:87], v[46:49], v[100:103], v[84:87]
	ds_read_b32 v63, v63
	ds_read_b128 v[88:91], v75
	v_cndmask_b32_e64 v64, v64, 1.0, s[72:73]
	s_or_b64 s[90:91], s[72:73], vcc
	s_waitcnt lgkmcnt(0)
	v_sub_f32_e32 v65, v63, v88
	v_min_f32_e32 v65, 0, v65
	v_sub_f32_e32 v76, v63, v89
	v_mul_f32_e32 v65, 0x3fb8aa3b, v65
	v_min_f32_e32 v76, 0, v76
	v_exp_f32_e32 v65, v65
	v_mul_f32_e32 v76, 0x3fb8aa3b, v76
	v_exp_f32_e32 v76, v76
	v_sub_f32_e32 v77, v63, v90
	v_min_f32_e32 v77, 0, v77
	v_mul_f32_e32 v65, v84, v65
	v_mul_f32_e32 v77, 0x3fb8aa3b, v77
	v_mul_f32_e32 v64, v64, v65
	v_cndmask_b32_e64 v65, 0, 1.0, s[90:91]
	v_mul_f32_e32 v76, v85, v76
	v_exp_f32_e32 v77, v77
	v_mul_f32_e32 v65, v65, v76
	v_or_b32_e32 v76, 2, v67
	v_sub_f32_e32 v63, v63, v91
	v_cmp_gt_i32_e32 vcc, v76, v83
	v_min_f32_e32 v63, 0, v63
	v_mul_f32_e32 v63, 0x3fb8aa3b, v63
	v_cndmask_b32_e64 v76, 1.0, 0, vcc
	v_cndmask_b32_e64 v76, v76, 1.0, s[72:73]
	v_mul_f32_e32 v77, v86, v77
	v_exp_f32_e32 v63, v63
	v_mul_f32_e32 v76, v76, v77
	v_or_b32_e32 v77, 3, v67
	v_cmp_gt_i32_e32 vcc, v77, v83
	v_mul_f32_e32 v63, v87, v63
	v_cvt_pk_bf16_f32 v64, v64, v65
	v_cndmask_b32_e64 v77, 1.0, 0, vcc
	v_cndmask_b32_e64 v77, v77, 1.0, s[72:73]
	v_mul_f32_e32 v63, v77, v63
	v_cvt_pk_bf16_f32 v65, v76, v63

; #define LAS __attribute__((address_space(3)))
; __device__ __forceinline__ u32x2_t pack4bf(f32x4 v) { u32x2_t r; r.x = pg8::cvt_pk_bf16(v[0], v[1]); r.y = pg8::cvt_pk_bf16(v[2], v[3]); return r; }
; __device__ __forceinline__ int frag_off(int row, int k, int ksteps) { return ((row >> 4) * ksteps + (k >> 5)) * 512 + (((k >> 3) & 3) * 16 + (row & 15)) * 8 + (k & 7); }
; template <int SKIP>
; __device__ __forceinline__ void p2_chunk_prep_fast(Frame& F, const Args& a) {
;     ...
;             for (int tj = 0; tj < 4; ++tj) {
;                 if (kind == 0) {
;                     if (tj > ti) continue;
;                     f32x4 acc = (f32x4){0.f, 0.f, 0.f, 0.f};
; #pragma unroll
;                     for (int ks = 0; ks < 4; ++ks) acc = __builtin_amdgcn_mfma_f32_16x16x32_bf16(af[ks], *(const LAS bf16x8_t*)(L + L_KS + (16 * tj + fr) * QS_LD + (32 * ks + 8 * fq) * 2), acc, 0, 0, 0);
;                     const int j = 16 * tj + fr; const float gj = gc[j]; const f32x4 gi4 = *(const LAS f32x4*)(gc + 16 * ti + 4 * fq), bi4 = *(const LAS f32x4*)(beta + 16 * ti + 4 * fq);
; #pragma unroll
;                     for (int r = 0; r < 4; ++r) { const int i = 16 * ti + 4 * fq + r; const float m = (tj < ti || fr < 4 * fq + r) ? 1.f : 0.f; Am[i * AM_LD + j] = acc[r] * bi4[r] * __expf(fminf(gi4[r] - gj, 0.f)) * m; }
;                 } else {
;                     const int i = 16 * tj + fr; u32x2_t o = (u32x2_t){0u, 0u};
;                     if (tj >= ti) {
;                         f32x4 acc = (f32x4){0.f, 0.f, 0.f, 0.f};
; #pragma unroll
;                         for (int ks = 0; ks < 4; ++ks) acc = __builtin_amdgcn_mfma_f32_16x16x32_bf16(af[ks], *(const LAS bf16x8_t*)(L + L_QS + (16 * tj + fr) * QS_LD + (32 * ks + 8 * fq) * 2), acc, 0, 0, 0);
;                         const float gi = gc[i]; const f32x4 gj4 = *(const LAS f32x4*)(gc + 16 * ti + 4 * fq);
; #pragma unroll
;                         for (int r = 0; r < 4; ++r) { const float m = (tj > ti || 4 * fq + r <= fr) ? 1.f : 0.f; acc[r] = acc[r] * __expf(fminf(gi - gj4[r], 0.f)) * m; }
;                         o = pack4bf(acc);
;                     }
;                     *(u32x2_t*)(oQK + frag_off(i, 16 * ti + 4 * fq, 2)) = o;
.LBB0_688:
	s_and_b64 vcc, exec, s[90:91]
	s_cbranch_vccz .LBB0_691
	v_readlane_b32 s90, v255, 49
	v_readlane_b32 s91, v255, 50
	s_andn2_b64 vcc, exec, s[90:91]
	s_cbranch_vccnz .LBB0_691
	v_or_b32_e32 v63, 32, v83
	v_mad_u32_u24 v64, v63, s28, v72
	ds_read_b128 v[84:87], v64 offset:17408
	ds_read_b128 v[88:91], v64 offset:17472
	ds_read_b128 v[96:99], v64 offset:17536
	ds_read_b128 v[100:103], v64 offset:17600
	v_lshlrev_b32_e32 v63, 2, v63
	v_cmp_lt_i32_e32 vcc, v83, v67
	s_or_b64 s[90:91], s[80:81], vcc
	s_waitcnt lgkmcnt(3)
	v_mfma_f32_16x16x32_bf16 v[84:87], v[58:61], v[84:87], 0
	v_cndmask_b32_e64 v65, 0, 1.0, s[90:91]
	v_cmp_le_i32_e32 vcc, v83, v67
	s_or_b64 s[90:91], s[80:81], vcc
	s_waitcnt lgkmcnt(2)
	v_mfma_f32_16x16x32_bf16 v[84:87], v[54:57], v[88:91], v[84:87]
	s_waitcnt lgkmcnt(1)
	v_mfma_f32_16x16x32_bf16 v[84:87], v[50:53], v[96:99], v[84:87]
	v_add_u32_e32 v64, 0, v63
	v_add_u32_e32 v64, 0x20500, v64
	s_waitcnt lgkmcnt(0)
	v_mfma_f32_16x16x32_bf16 v[84:87], v[46:49], v[100:103], v[84:87]
	ds_read_b32 v64, v64
	ds_read_b128 v[88:91], v73
	ds_read_b128 v[92:95], v74
	s_waitcnt lgkmcnt(1)
	v_sub_f32_e32 v77, v88, v64
	v_min_f32_e32 v77, 0, v77
	v_mul_f32_e32 v77, 0x3fb8aa3b, v77
	v_sub_f32_e32 v78, v89, v64
	v_exp_f32_e32 v77, v77
	v_min_f32_e32 v78, 0, v78
	v_mul_f32_e32 v78, 0x3fb8aa3b, v78
	v_exp_f32_e32 v78, v78
	s_waitcnt lgkmcnt(0)
	v_mul_f32_e32 v76, v84, v92
	v_mul_f32_e32 v76, v76, v77
	v_mul_f32_e32 v65, v65, v76
	v_mul_lo_u32 v76, v69, s28
	v_mul_f32_e32 v77, v85, v93
	v_add3_u32 v63, s29, v76, v63
	v_cndmask_b32_e64 v76, 0, 1.0, s[90:91]
	v_mul_f32_e32 v77, v77, v78
	v_mul_f32_e32 v76, v76, v77
	v_sub_f32_e32 v77, v90, v64
	v_min_f32_e32 v77, 0, v77
	v_mul_f32_e32 v77, 0x3fb8aa3b, v77
	v_exp_f32_e32 v77, v77
	ds_write2_b32 v63, v65, v76 offset1:68
	v_or_b32_e32 v65, 2, v67
	v_sub_f32_e32 v64, v91, v64
	v_cmp_lt_i32_e32 vcc, v83, v65
	v_min_f32_e32 v64, 0, v64
	s_or_b64 s[90:91], s[80:81], vcc
	v_mul_f32_e32 v76, v86, v94
	v_mul_f32_e32 v64, 0x3fb8aa3b, v64
	v_cndmask_b32_e64 v65, 0, 1.0, s[90:91]
	v_mul_f32_e32 v76, v76, v77
	v_exp_f32_e32 v64, v64
	v_mul_f32_e32 v65, v65, v76
	v_or_b32_e32 v76, 3, v67
	v_cmp_lt_i32_e32 vcc, v83, v76
	s_or_b64 s[90:91], s[80:81], vcc
	v_mul_f32_e32 v77, v87, v95
	v_cndmask_b32_e64 v76, 0, 1.0, s[90:91]
	v_mul_f32_e32 v64, v77, v64
	v_mul_f32_e32 v64, v76, v64
	ds_write2_b32 v63, v65, v64 offset0:136 offset1:204
.LBB0_691:
	s_and_b64 vcc, exec, s[6:7]
	s_mov_b64 s[6:7], -1
	s_cbranch_vccnz .LBB0_693
	v_or_b32_e32 v63, 48, v83
	v_mad_u32_u24 v64, v63, s28, v72
	ds_read_b128 v[84:87], v64
	ds_read_b128 v[88:91], v64 offset:64
	ds_read_b128 v[96:99], v64 offset:128
	ds_read_b128 v[100:103], v64 offset:192
	v_lshl_add_u32 v63, v63, 2, 0
	v_add_u32_e32 v63, 0x20500, v63
	v_cmp_gt_i32_e32 vcc, v67, v83
	s_waitcnt lgkmcnt(3)
	v_mfma_f32_16x16x32_bf16 v[84:87], v[58:61], v[84:87], 0
	s_and_b64 s[6:7], s[4:5], vcc
	v_cmp_lt_i32_e32 vcc, v67, v83
	v_add_u32_e32 v62, 0xc00, v62
	s_waitcnt lgkmcnt(2)
	v_mfma_f32_16x16x32_bf16 v[84:87], v[54:57], v[88:91], v[84:87]
	s_waitcnt lgkmcnt(1)
	v_mfma_f32_16x16x32_bf16 v[84:87], v[50:53], v[96:99], v[84:87]
	v_cndmask_b32_e64 v64, 1.0, 0, s[6:7]
	s_waitcnt lgkmcnt(0)
	v_mfma_f32_16x16x32_bf16 v[84:87], v[46:49], v[100:103], v[84:87]
	ds_read_b32 v63, v63
	ds_read_b128 v[88:91], v75
	s_waitcnt lgkmcnt(0)
	v_sub_f32_e32 v65, v63, v88
	v_min_f32_e32 v65, 0, v65
	v_mul_f32_e32 v65, 0x3fb8aa3b, v65
	v_sub_f32_e32 v75, v63, v89
	v_exp_f32_e32 v65, v65
	v_min_f32_e32 v75, 0, v75
	v_mul_f32_e32 v75, 0x3fb8aa3b, v75
	v_exp_f32_e32 v75, v75
	v_mul_f32_e32 v65, v84, v65
	v_mul_f32_e32 v64, v64, v65
	v_cndmask_b32_e64 v65, 0, 1.0, vcc
	v_cndmask_b32_e64 v65, 1.0, v65, s[4:5]
	v_mul_f32_e32 v75, v85, v75
	v_mul_f32_e32 v65, v65, v75
	v_sub_f32_e32 v75, v63, v90
	v_min_f32_e32 v75, 0, v75
	v_mul_f32_e32 v75, 0x3fb8aa3b, v75
	v_exp_f32_e32 v75, v75
	v_cvt_pk_bf16_f32 v64, v64, v65
	v_or_b32_e32 v65, 2, v67
	v_sub_f32_e32 v63, v63, v91
	v_cmp_gt_i32_e32 vcc, v65, v83
	v_min_f32_e32 v63, 0, v63
	s_and_b64 s[6:7], s[4:5], vcc
	v_mul_f32_e32 v63, 0x3fb8aa3b, v63
	v_cndmask_b32_e64 v65, 1.0, 0, s[6:7]
	v_mul_f32_e32 v75, v86, v75
	v_exp_f32_e32 v63, v63
	v_mul_f32_e32 v65, v65, v75
	v_or_b32_e32 v75, 3, v67
	v_cmp_gt_i32_e32 vcc, v75, v83
	s_and_b64 s[6:7], s[4:5], vcc
	v_cndmask_b32_e64 v75, 1.0, 0, s[6:7]
	v_mul_f32_e32 v63, v87, v63
	v_mul_f32_e32 v63, v75, v63
	v_cvt_pk_bf16_f32 v65, v65, v63
	v_ashrrev_i32_e32 v63, 31, v62
	v_lshl_add_u64 v[62:63], v[62:63], 1, s[88:89]
	s_mov_b64 s[6:7], 0
	global_store_dwordx2 v[62:63], v[64:65], off
